# barrier: local workgroups poll the cross-XCD generation word directly (one release hop)
# speedup vs baseline: 1.0175x; 1.0052x over previous
; __device__ __forceinline__ unsigned xb_ld(unsigned* p)              { return __hip_atomic_load(p, __ATOMIC_RELAXED, __HIP_MEMORY_SCOPE_AGENT); }
; __device__ __forceinline__ unsigned xb_add(unsigned* p, unsigned v) { return __hip_atomic_fetch_add(p, v, __ATOMIC_RELAXED, __HIP_MEMORY_SCOPE_AGENT); }
; #define XB_SPIN(cond, bar) do { unsigned _sp = 0; while (cond) { __builtin_amdgcn_s_sleep(1); \
;     if ((++_sp & 255u) == 0u) { if (xb_ld(&(bar)[XB_TMO])) break; if (_sp > XB_SPIN_CAP) { atomicAdd(&(bar)[XB_TMO], 1u); break; } } } } while (0)
; __device__ __forceinline__ void xcd_barrier(const XcdBarrier& b) {
;     ...
;     const unsigned old = xb_add(&bar[XB_XSUB(b.x)], 1u);
;     const unsigned gen = old / nloc;
;     if (old + 1u == (gen + 1u) * nloc) {
;       __builtin_amdgcn_fence(__ATOMIC_RELEASE, "agent");
;       asm volatile("s_waitcnt vmcnt(0)" ::: "memory");
;       const unsigned og = xb_add(&bar[XB_TOP], 1u);
;       const unsigned tg = og / nx;
;       if (og + 1u == (tg + 1u) * nx) xb_add(&bar[XB_TOPGEN], 1u);
;       else XB_SPIN(xb_ld(&bar[XB_TOPGEN]) == tg, bar);
;       __builtin_amdgcn_fence(__ATOMIC_ACQUIRE, "agent");
;       xb_add(&bar[XB_XGEN(b.x)], 1u);
;       asm volatile("s_waitcnt vmcnt(0)" ::: "memory");
;     } else {
;       XB_SPIN(xb_ld(&bar[XB_XGEN(b.x)]) == gen, bar);
.LBB0_1967:
	s_or_b64 exec, exec, s[8:9]
	v_cvt_f32_u32_e32 v5, v3
	s_waitcnt vmcnt(0)
	v_readfirstlane_b32 s8, v4
	v_sub_u32_e32 v4, 0, v3
	v_rcp_iflag_f32_e32 v5, v5
	v_add_u32_e32 v6, s8, v0
	v_mul_f32_e32 v5, 0x4f7ffffe, v5
	v_cvt_u32_f32_e32 v5, v5
	v_mul_lo_u32 v0, v4, v5
	v_mul_hi_u32 v0, v5, v0
	v_add_u32_e32 v0, v5, v0
	v_mul_hi_u32 v0, v6, v0
	v_mul_lo_u32 v4, v0, v3
	v_sub_u32_e32 v4, v6, v4
	v_add_u32_e32 v5, 1, v0
	v_cmp_ge_u32_e32 vcc, v4, v3
	s_nop 1
	v_cndmask_b32_e32 v0, v0, v5, vcc
	v_sub_u32_e32 v5, v4, v3
	v_cndmask_b32_e32 v4, v4, v5, vcc
	v_add_u32_e32 v5, 1, v0
	v_cmp_ge_u32_e32 vcc, v4, v3
	v_add_u32_e32 v4, 1, v6
	s_nop 0
	v_cndmask_b32_e32 v0, v0, v5, vcc
	v_mul_lo_u32 v5, v3, v0
	v_add_u32_e32 v3, v5, v3
	v_cmp_ne_u32_e32 vcc, v4, v3
	s_and_saveexec_b64 s[8:9], vcc
	s_xor_b64 s[8:9], exec, s[8:9]
	s_cbranch_execz .LBB0_1981
	v_readlane_b32 s10, v252, 52
	v_readlane_b32 s11, v252, 53
	s_waitcnt lgkmcnt(0)
	s_nop 3
	global_load_dword v2, v1, s[10:11] sc1
	s_waitcnt vmcnt(0)
	v_cmp_eq_u32_e32 vcc, v2, v0
	s_and_saveexec_b64 s[10:11], vcc
	s_cbranch_execz .LBB0_1980
	s_mov_b32 s28, 1
	s_mov_b64 s[12:13], 0
	s_branch .LBB0_1971
